# L1 neighbourhood-attention window loop: the 32 serialized bias ds_read_b32 (+lgkmcnt(0) each) replaced by a 6-deep rolling pipeline with counted lgkmcnt; on top of v14
# baseline (speedup 1.0000x reference)
.LBB0_422:
	s_mul_i32 s19, s20, 0x4c00
	v_add_u32_e32 v0, s19, v157
	ds_read_b128 v[206:209], v0
	ds_read_b128 v[210:213], v0 offset:4608
	ds_read_b128 v[214:217], v0 offset:32
	s_waitcnt lgkmcnt(2)
	v_mfma_f32_32x32x16_bf16 v[50:65], v[206:209], v[66:69], v[220:235]
	v_add_f32_e64 v90, v116, 0
	v_add_f32_e64 v91, v117, 0
	v_cvt_pk_bf16_f32 v102, v116, v117
	v_add_f32_e64 v90, v118, v90
	v_add_f32_e64 v91, v119, v91
	v_cvt_pk_bf16_f32 v103, v118, v119
	s_waitcnt lgkmcnt(1)
	v_mfma_f32_32x32x16_bf16 v[34:49], v[210:213], v[66:69], v[220:235]
	ds_read_b128 v[116:119], v0 offset:4640
	v_add_f32_e64 v90, v104, v90
	v_add_f32_e64 v91, v105, v91
	v_cvt_pk_bf16_f32 v104, v104, v105
	v_add_f32_e64 v90, v120, v90
	v_add_f32_e64 v91, v121, v91
	v_cvt_pk_bf16_f32 v105, v120, v121
	s_waitcnt lgkmcnt(1)
	v_mfma_f32_32x32x16_bf16 v[50:65], v[214:217], v[70:73], v[50:65]
	ds_read_b128 v[206:209], v0 offset:64
	v_add_f32_e64 v90, v122, v90
	v_add_f32_e64 v91, v123, v91
	v_cvt_pk_bf16_f32 v98, v122, v123
	v_add_f32_e64 v90, v126, v90
	v_add_f32_e64 v91, v127, v91
	v_cvt_pk_bf16_f32 v99, v126, v127
	s_waitcnt lgkmcnt(1)
	v_mfma_f32_32x32x16_bf16 v[34:49], v[116:119], v[70:73], v[34:49]
	ds_read_b128 v[120:123], v0 offset:4672
	v_add_f32_e64 v90, v100, v90
	v_add_f32_e64 v91, v101, v91
	v_cvt_pk_bf16_f32 v100, v100, v101
	v_add_f32_e64 v90, v130, v90
	v_add_f32_e64 v91, v131, v91
	v_cvt_pk_bf16_f32 v101, v130, v131
	s_waitcnt lgkmcnt(1)
	v_mfma_f32_32x32x16_bf16 v[50:65], v[206:209], v[74:77], v[50:65]
	ds_read_b128 v[116:119], v0 offset:96
	v_add_f32_e64 v90, v124, v90
	v_add_f32_e64 v91, v125, v91
	v_cvt_pk_bf16_f32 v94, v124, v125
	v_add_f32_e64 v90, v128, v90
	v_add_f32_e64 v91, v129, v91
	v_cvt_pk_bf16_f32 v95, v128, v129
	s_waitcnt lgkmcnt(1)
	v_mfma_f32_32x32x16_bf16 v[34:49], v[120:123], v[74:77], v[34:49]
	ds_read_b128 v[124:127], v0 offset:4704
	v_add_f32_e64 v90, v96, v90
	v_add_f32_e64 v91, v97, v91
	v_cvt_pk_bf16_f32 v96, v96, v97
	v_add_f32_e64 v90, v132, v90
	v_add_f32_e64 v91, v133, v91
	v_cvt_pk_bf16_f32 v97, v132, v133
	s_waitcnt lgkmcnt(1)
	v_mfma_f32_32x32x16_bf16 v[50:65], v[116:119], v[78:81], v[50:65]
	v_add_f32_e64 v116, v134, v90
	v_add_f32_e64 v117, v135, v91
	v_cvt_pk_bf16_f32 v90, v134, v135
	v_add_f32_e64 v116, v136, v116
	v_add_f32_e64 v117, v137, v117
	v_cvt_pk_bf16_f32 v91, v136, v137
	s_waitcnt lgkmcnt(0)
	v_mfma_f32_32x32x16_bf16 v[34:49], v[124:127], v[78:81], v[34:49]
	v_add_f32_e64 v116, v92, v116
	v_add_f32_e64 v117, v93, v117
	v_cvt_pk_bf16_f32 v92, v92, v93
	v_add_f32_e64 v116, v138, v116
	v_add_f32_e64 v117, v139, v117
	v_cvt_pk_bf16_f32 v93, v138, v139
	s_cmp_lt_u32 s7, 8
	s_cbranch_scc1 .LBB0_424
	s_add_i32 s6, s16, s17
	s_addk_i32 s6, 0xfe40
	s_ashr_i32 s22, s6, 6
	v_sub_u32_e32 v0, s22, v159
	v_mul_lo_u32 v0, v0, 31
	v_sub_u32_e32 v0, v0, v150
	v_add_u32_e32 v0, 0xe8, v0
	v_add_u32_e32 v118, v0, v161
	v_med3_i32 v118, v118, 0, v204
	v_lshl_add_u32 v118, v118, 2, v203
	ds_read_b32 v118, v118
	v_add_u32_e32 v218, v0, v163
	v_med3_i32 v218, v218, 0, v204
	v_lshl_add_u32 v218, v218, 2, v203
	ds_read_b32 v218, v218
	v_add_u32_e32 v219, v0, v164
	v_med3_i32 v219, v219, 0, v204
	v_lshl_add_u32 v219, v219, 2, v203
	ds_read_b32 v219, v219
	v_add_u32_e32 v236, v0, v165
	v_med3_i32 v236, v236, 0, v204
	v_lshl_add_u32 v236, v236, 2, v203
	ds_read_b32 v236, v236
	v_add_u32_e32 v237, v0, v166
	v_med3_i32 v237, v237, 0, v204
	v_lshl_add_u32 v237, v237, 2, v203
	ds_read_b32 v237, v237
	v_add_u32_e32 v238, v0, v167
	v_med3_i32 v238, v238, 0, v204
	v_lshl_add_u32 v238, v238, 2, v203
	ds_read_b32 v238, v238
	v_cmp_ge_i32_e64 s[6:7], s22, v160
	v_cmp_lt_i32_e32 vcc, s22, v162
	s_and_b64 s[6:7], s[6:7], vcc
	s_and_b64 vcc, s[6:7], s[36:37]
	s_waitcnt lgkmcnt(5)
	v_add_f32_e32 v50, v50, v118
	v_cndmask_b32_e32 v50, v201, v50, vcc
	v_add_u32_e32 v118, v0, v168
	v_med3_i32 v118, v118, 0, v204
	v_lshl_add_u32 v118, v118, 2, v203
	ds_read_b32 v118, v118
	s_and_b64 vcc, s[6:7], s[38:39]
	s_waitcnt lgkmcnt(5)
	v_add_f32_e32 v51, v51, v218
	v_cndmask_b32_e32 v51, v201, v51, vcc
	v_add_u32_e32 v218, v0, v169
	v_med3_i32 v218, v218, 0, v204
	v_lshl_add_u32 v218, v218, 2, v203
	ds_read_b32 v218, v218
	s_and_b64 vcc, s[6:7], s[40:41]
	s_waitcnt lgkmcnt(5)
	v_add_f32_e32 v52, v52, v219
	v_cndmask_b32_e32 v52, v201, v52, vcc
	v_add_u32_e32 v219, v0, v170
	v_med3_i32 v219, v219, 0, v204
	v_lshl_add_u32 v219, v219, 2, v203
	ds_read_b32 v219, v219
	s_and_b64 vcc, s[6:7], s[42:43]
	s_waitcnt lgkmcnt(5)
	v_add_f32_e32 v53, v53, v236
	v_cndmask_b32_e32 v53, v201, v53, vcc
	v_add_u32_e32 v236, v0, v171
	v_med3_i32 v236, v236, 0, v204
	v_lshl_add_u32 v236, v236, 2, v203
	ds_read_b32 v236, v236
	s_and_b64 vcc, s[6:7], s[44:45]
	s_waitcnt lgkmcnt(5)
	v_add_f32_e32 v54, v54, v237
	v_cndmask_b32_e32 v54, v201, v54, vcc
	v_add_u32_e32 v237, v0, v172
	v_med3_i32 v237, v237, 0, v204
	v_lshl_add_u32 v237, v237, 2, v203
	ds_read_b32 v237, v237
	s_and_b64 vcc, s[6:7], s[46:47]
	s_waitcnt lgkmcnt(5)
	v_add_f32_e32 v55, v55, v238
	v_cndmask_b32_e32 v55, v201, v55, vcc
	v_add_u32_e32 v238, v0, v173
	v_med3_i32 v238, v238, 0, v204
	v_lshl_add_u32 v238, v238, 2, v203
	ds_read_b32 v238, v238
	s_and_b64 vcc, s[6:7], s[10:11]
	s_waitcnt lgkmcnt(5)
	v_add_f32_e32 v56, v56, v118
	v_cndmask_b32_e32 v56, v201, v56, vcc
	v_add_u32_e32 v118, v0, v174
	v_med3_i32 v118, v118, 0, v204
	v_lshl_add_u32 v118, v118, 2, v203
	ds_read_b32 v118, v118
	s_and_b64 vcc, s[6:7], s[50:51]
	s_waitcnt lgkmcnt(5)
	v_add_f32_e32 v57, v57, v218
	v_cndmask_b32_e32 v57, v201, v57, vcc
	v_add_u32_e32 v218, v0, v175
	v_med3_i32 v218, v218, 0, v204
	v_lshl_add_u32 v218, v218, 2, v203
	ds_read_b32 v218, v218
	s_and_b64 vcc, s[6:7], s[52:53]
	s_waitcnt lgkmcnt(5)
	v_add_f32_e32 v58, v58, v219
	v_cndmask_b32_e32 v58, v201, v58, vcc
	v_add_u32_e32 v219, v0, v176
	v_med3_i32 v219, v219, 0, v204
	v_lshl_add_u32 v219, v219, 2, v203
	ds_read_b32 v219, v219
	s_and_b64 vcc, s[6:7], s[54:55]
	s_waitcnt lgkmcnt(5)
	v_add_f32_e32 v59, v59, v236
	v_cndmask_b32_e32 v59, v201, v59, vcc
	v_add_u32_e32 v236, v0, v177
	v_med3_i32 v236, v236, 0, v204
	v_lshl_add_u32 v236, v236, 2, v203
	ds_read_b32 v236, v236
	s_and_b64 vcc, s[6:7], s[56:57]
	s_waitcnt lgkmcnt(5)
	v_add_f32_e32 v60, v60, v237
	v_cndmask_b32_e32 v60, v201, v60, vcc
	v_add_u32_e32 v237, v0, v178
	v_med3_i32 v237, v237, 0, v204
	v_lshl_add_u32 v237, v237, 2, v203
	ds_read_b32 v237, v237
	s_and_b64 vcc, s[6:7], s[58:59]
	s_waitcnt lgkmcnt(5)
	v_add_f32_e32 v61, v61, v238
	v_cndmask_b32_e32 v61, v201, v61, vcc
	v_add_u32_e32 v238, v0, v179
	v_med3_i32 v238, v238, 0, v204
	v_lshl_add_u32 v238, v238, 2, v203
	ds_read_b32 v238, v238
	s_and_b64 vcc, s[6:7], s[60:61]
	s_waitcnt lgkmcnt(5)
	v_add_f32_e32 v62, v62, v118
	v_cndmask_b32_e32 v62, v201, v62, vcc
	v_add_u32_e32 v118, v0, v180
	v_med3_i32 v118, v118, 0, v204
	v_lshl_add_u32 v118, v118, 2, v203
	ds_read_b32 v118, v118
	s_and_b64 vcc, s[6:7], s[62:63]
	s_waitcnt lgkmcnt(5)
	v_add_f32_e32 v63, v63, v218
	v_cndmask_b32_e32 v63, v201, v63, vcc
	v_add_u32_e32 v218, v0, v181
	v_med3_i32 v218, v218, 0, v204
	v_lshl_add_u32 v218, v218, 2, v203
	ds_read_b32 v218, v218
	s_and_b64 vcc, s[6:7], s[64:65]
	s_waitcnt lgkmcnt(5)
	v_add_f32_e32 v64, v64, v219
	v_cndmask_b32_e32 v64, v201, v64, vcc
	v_add_u32_e32 v219, v0, v182
	v_med3_i32 v219, v219, 0, v204
	v_lshl_add_u32 v219, v219, 2, v203
	ds_read_b32 v219, v219
	s_and_b64 vcc, s[6:7], s[66:67]
	s_waitcnt lgkmcnt(5)
	v_add_f32_e32 v65, v65, v236
	v_cndmask_b32_e32 v65, v201, v65, vcc
	v_add_u32_e32 v236, v0, v183
	v_med3_i32 v236, v236, 0, v204
	v_lshl_add_u32 v236, v236, 2, v203
	ds_read_b32 v236, v236
	s_and_b64 vcc, s[6:7], s[68:69]
	s_waitcnt lgkmcnt(5)
	v_add_f32_e32 v34, v34, v237
	v_cndmask_b32_e32 v34, v201, v34, vcc
	v_add_u32_e32 v237, v0, v184
	v_med3_i32 v237, v237, 0, v204
	v_lshl_add_u32 v237, v237, 2, v203
	ds_read_b32 v237, v237
	s_and_b64 vcc, s[6:7], s[70:71]
	s_waitcnt lgkmcnt(5)
	v_add_f32_e32 v35, v35, v238
	v_cndmask_b32_e32 v35, v201, v35, vcc
	v_add_u32_e32 v238, v0, v185
	v_med3_i32 v238, v238, 0, v204
	v_lshl_add_u32 v238, v238, 2, v203
	ds_read_b32 v238, v238
	s_and_b64 vcc, s[6:7], s[72:73]
	s_waitcnt lgkmcnt(5)
	v_add_f32_e32 v36, v36, v118
	v_cndmask_b32_e32 v36, v201, v36, vcc
	v_add_u32_e32 v118, v0, v186
	v_med3_i32 v118, v118, 0, v204
	v_lshl_add_u32 v118, v118, 2, v203
	ds_read_b32 v118, v118
	s_and_b64 vcc, s[6:7], s[74:75]
	s_waitcnt lgkmcnt(5)
	v_add_f32_e32 v37, v37, v218
	v_cndmask_b32_e32 v37, v201, v37, vcc
	v_add_u32_e32 v218, v0, v187
	v_med3_i32 v218, v218, 0, v204
	v_lshl_add_u32 v218, v218, 2, v203
	ds_read_b32 v218, v218
	s_and_b64 vcc, s[6:7], s[76:77]
	s_waitcnt lgkmcnt(5)
	v_add_f32_e32 v38, v38, v219
	v_cndmask_b32_e32 v38, v201, v38, vcc
	v_add_u32_e32 v219, v0, v188
	v_med3_i32 v219, v219, 0, v204
	v_lshl_add_u32 v219, v219, 2, v203
	ds_read_b32 v219, v219
	s_and_b64 vcc, s[6:7], s[78:79]
	s_waitcnt lgkmcnt(5)
	v_add_f32_e32 v39, v39, v236
	v_cndmask_b32_e32 v39, v201, v39, vcc
	v_add_u32_e32 v236, v0, v189
	v_med3_i32 v236, v236, 0, v204
	v_lshl_add_u32 v236, v236, 2, v203
	ds_read_b32 v236, v236
	s_and_b64 vcc, s[6:7], s[0:1]
	s_waitcnt lgkmcnt(5)
	v_add_f32_e32 v40, v40, v237
	v_cndmask_b32_e32 v40, v201, v40, vcc
	v_add_u32_e32 v237, v0, v190
	v_med3_i32 v237, v237, 0, v204
	v_lshl_add_u32 v237, v237, 2, v203
	ds_read_b32 v237, v237
	s_and_b64 vcc, s[6:7], s[82:83]
	s_waitcnt lgkmcnt(5)
	v_add_f32_e32 v41, v41, v238
	v_cndmask_b32_e32 v41, v201, v41, vcc
	v_add_u32_e32 v238, v0, v191
	v_med3_i32 v238, v238, 0, v204
	v_lshl_add_u32 v238, v238, 2, v203
	ds_read_b32 v238, v238
	s_and_b64 vcc, s[6:7], s[84:85]
	s_waitcnt lgkmcnt(5)
	v_add_f32_e32 v42, v42, v118
	v_cndmask_b32_e32 v42, v201, v42, vcc
	v_add_u32_e32 v118, v0, v192
	v_med3_i32 v118, v118, 0, v204
	v_lshl_add_u32 v118, v118, 2, v203
	ds_read_b32 v118, v118
	s_and_b64 vcc, s[6:7], s[86:87]
	s_waitcnt lgkmcnt(5)
	v_add_f32_e32 v43, v43, v218
	v_cndmask_b32_e32 v43, v201, v43, vcc
	v_add_u32_e32 v218, v0, v193
	v_med3_i32 v218, v218, 0, v204
	v_lshl_add_u32 v218, v218, 2, v203
	ds_read_b32 v218, v218
	s_and_b64 vcc, s[6:7], s[88:89]
	s_waitcnt lgkmcnt(5)
	v_add_f32_e32 v44, v44, v219
	v_cndmask_b32_e32 v44, v201, v44, vcc
	s_and_b64 vcc, s[6:7], s[90:91]
	s_waitcnt lgkmcnt(4)
	v_add_f32_e32 v45, v45, v236
	v_cndmask_b32_e32 v45, v201, v45, vcc
	s_and_b64 vcc, s[6:7], s[92:93]
	s_waitcnt lgkmcnt(3)
	v_add_f32_e32 v46, v46, v237
	v_cndmask_b32_e32 v46, v201, v46, vcc
	s_and_b64 vcc, s[6:7], s[94:95]
	s_waitcnt lgkmcnt(2)
	v_add_f32_e32 v47, v47, v238
	v_cndmask_b32_e32 v47, v201, v47, vcc
	s_and_b64 vcc, s[6:7], s[96:97]
	s_waitcnt lgkmcnt(1)
	v_add_f32_e32 v48, v48, v118
	v_cndmask_b32_e32 v48, v201, v48, vcc
	s_and_b64 vcc, s[6:7], s[4:5]
	s_waitcnt lgkmcnt(0)
	v_add_f32_e32 v49, v49, v218
	v_cndmask_b32_e32 v49, v201, v49, vcc
